# differential unit prologue: Q loads and the diagonal K/V LDS-DMA issued in front of the norm-bound wait and sqrt/div chain
# speedup vs baseline: 1.0016x; 1.0016x over previous
.LBB0_443:
	s_lshr_b32 s2, s15, 6
	s_ashr_i32 s78, s15, 8
	s_add_i32 s2, s2, s78
	s_and_b32 s10, s2, 3
	s_mul_i32 s3, s78, 23
	s_not_b32 s2, s10
	s_add_i32 s3, s3, s15
	s_lshl_b32 s4, s2, 1
	s_lshl_b32 s2, s78, 5
	s_and_b32 s48, s3, 63
	s_ashr_i32 s3, s2, 31
	s_lshl_b32 s34, s48, 7
	s_lshl_b64 s[2:3], s[2:3], 2
	s_add_u32 s2, s1, s2
	s_addc_u32 s3, s6, s3
	s_lshl_b32 s5, s10, 4
	v_mov_b32_e32 v0, s5
	global_load_dwordx4 v[2:5], v0, s[2:3]
	global_load_dwordx4 v[6:9], v0, s[2:3] offset:64
	v_cvt_f32_i32_e32 v0, s4
	s_ashr_i32 s79, s78, 31
	s_lshl_b64 s[2:3], s[78:79], 13
	v_or_b32_e32 v34, s34, v215
	v_or_b32_e32 v196, s2, v34
	v_mov_b32_e32 v197, s3
	v_lshlrev_b64 v[20:21], 12, v[196:197]
	s_lshl_b32 s57, s10, 7
	s_lshl_b32 s10, s10, 8
	v_lshl_add_u64 v[20:21], s[22:23], 0, v[20:21]
	v_lshl_add_u64 v[20:21], v[20:21], 0, s[10:11]
	s_mov_b32 s39, s11
	v_lshl_add_u64 v[20:21], v[20:21], 0, s[38:39]
	v_mov_b32_e32 v183, v153
	v_lshl_add_u64 v[20:21], v[20:21], 0, v[182:183]
	global_load_dwordx4 v[130:133], v[20:21], off
	global_load_dwordx4 v[134:137], v[20:21], off offset:32
	global_load_dwordx4 v[138:141], v[20:21], off offset:64
	global_load_dwordx4 v[142:145], v[20:21], off offset:96
	v_lshl_add_u64 v[24:25], s[2:3], 0, v[150:151]
	v_lshlrev_b64 v[24:25], 12, v[24:25]
	v_lshl_add_u64 v[24:25], s[22:23], 0, v[24:25]
	v_lshl_add_u64 v[24:25], v[24:25], 0, s[10:11]
	v_lshl_add_u64 v[202:203], v[24:25], 0, v[152:153]
	v_add_u32_e32 v22, s57, v216
	v_mov_b64_e32 v[24:25], s[28:29]
	v_mad_u64_u32 v[26:27], s[2:3], v22, s42, v[24:25]
	v_add_u32_e32 v22, s57, v217
	s_lshl_b64 s[2:3], s[78:79], 14
	v_mad_u64_u32 v[24:25], s[60:61], v22, s42, v[24:25]
	v_lshl_add_u64 v[26:27], v[26:27], 0, s[2:3]
	v_lshl_add_u64 v[24:25], v[24:25], 0, s[2:3]
	v_mov_b32_e32 v181, v153
	s_lshl_b32 s2, s34, 12
	s_mov_b32 s3, s11
	v_mov_b32_e32 v179, v153
	v_lshl_add_u64 v[206:207], v[24:25], 0, v[180:181]
	v_lshl_add_u64 v[24:25], v[202:203], 0, s[2:3]
	s_mov_b32 m0, s7
	v_lshl_add_u64 v[204:205], v[26:27], 0, v[178:179]
	v_lshl_add_u64 v[26:27], v[24:25], 0, s[30:31]
	s_add_i32 s3, s7, 0x2000
	s_or_b32 s2, s34, 64
	global_load_lds_dwordx4 v[26:27], off
	v_lshl_add_u64 v[24:25], v[24:25], 0, s[36:37]
	s_mov_b32 m0, s3
	s_lshl_b32 s60, s2, 12
	s_mov_b32 s61, s11
	global_load_lds_dwordx4 v[24:25], off
	v_lshl_add_u64 v[24:25], v[202:203], 0, s[60:61]
	v_lshl_add_u64 v[26:27], v[24:25], 0, s[30:31]
	s_mov_b32 m0, s43
	global_load_lds_dwordx4 v[26:27], off
	v_lshl_add_u64 v[24:25], v[24:25], 0, s[36:37]
	s_mov_b32 m0, s49
	s_lshl_b32 s62, s34, 1
	global_load_lds_dwordx4 v[24:25], off
	s_mov_b32 s63, s11
	v_lshl_add_u64 v[44:45], v[204:205], 0, s[62:63]
	s_mov_b32 m0, s52
	v_lshl_add_u64 v[46:47], v[206:207], 0, s[62:63]
	global_load_lds_dwordx4 v[44:45], off
	s_mov_b32 m0, s53
	s_nop 0
	global_load_lds_dwordx4 v[46:47], off
	s_waitcnt vmcnt(11)
	v_mov_b32_e32 v10, v2
	s_waitcnt vmcnt(10)
	v_mov_b32_e32 v11, v6
	v_mov_b32_e32 v6, v3
	v_mov_b32_e32 v2, v4
	v_mov_b32_e32 v3, v8
	v_mov_b32_e32 v8, v5
	v_pk_add_f32 v[4:5], v[10:11], v[6:7]
	v_pk_add_f32 v[2:3], v[2:3], v[8:9]
	v_mul_f32_e32 v4, v4, v5
	v_mul_f32_e32 v2, v2, v3
	v_mul_f32_e32 v3, 0x4f800000, v4
	v_cmp_gt_f32_e32 vcc, s35, v4
	v_mul_f32_e32 v5, 0x4f800000, v2
	v_cmp_gt_f32_e64 s[2:3], s35, v2
	v_cndmask_b32_e32 v4, v4, v3, vcc
	v_sqrt_f32_e32 v6, v4
	v_cndmask_b32_e64 v2, v2, v5, s[2:3]
	v_sqrt_f32_e32 v5, v2
	v_exp_f32_e32 v3, v0
	v_add_u32_e32 v0, -1, v6
	v_fma_f32 v10, -v0, v6, v4
	v_add_u32_e32 v8, -1, v5
	v_add_u32_e32 v7, 1, v6
	v_fma_f32 v12, -v8, v5, v2
	v_cmp_ge_f32_e64 s[4:5], 0, v10
	v_add_u32_e32 v9, 1, v5
	v_fma_f32 v11, -v7, v6, v4
	v_cndmask_b32_e64 v0, v6, v0, s[4:5]
	v_cmp_ge_f32_e64 s[4:5], 0, v12
	v_fma_f32 v13, -v9, v5, v2
	s_nop 0
	v_cndmask_b32_e64 v5, v5, v8, s[4:5]
	v_cmp_lt_f32_e64 s[4:5], 0, v11
	s_nop 1
	v_cndmask_b32_e64 v0, v0, v7, s[4:5]
	v_cmp_lt_f32_e64 s[4:5], 0, v13
	v_mul_f32_e32 v6, 0x37800000, v0
	v_cndmask_b32_e32 v0, v0, v6, vcc
	v_cndmask_b32_e64 v5, v5, v9, s[4:5]
	v_mul_f32_e32 v7, 0x37800000, v5
	v_cmp_class_f32_e32 vcc, v4, v222
	v_cndmask_b32_e64 v5, v5, v7, s[2:3]
	s_nop 0
	v_cndmask_b32_e32 v0, v0, v4, vcc
	v_cmp_class_f32_e32 vcc, v2, v222
	s_nop 1
	v_cndmask_b32_e32 v2, v5, v2, vcc
	v_max3_f32 v0, v0, 0, v2
	v_mul_f32_e32 v2, 0x3f828f5c, v0
	v_cmp_gt_f32_e32 vcc, 0x42200000, v2
	s_cmp_lg_u64 vcc, 0
	s_cselect_b32 s98, 1, 0
	s_mov_b32 s99, 0
	v_pk_mul_f32 v[200:201], v[2:3], s[8:9]
	s_nop 0
	v_add_f32_e32 v0, 0x432a0000, v200
	v_div_scale_f32 v2, s[2:3], v201, v201, v0
	v_rcp_f32_e32 v3, v2
	v_div_scale_f32 v4, vcc, v0, v201, v0
	s_mov_b32 s2, 0x46000000
	v_fma_f32 v5, -v2, v3, 1.0
	v_fmac_f32_e32 v3, v5, v3
	v_mul_f32_e32 v5, v4, v3
	v_fma_f32 v6, -v2, v5, v4
	v_fmac_f32_e32 v5, v6, v3
	v_fma_f32 v2, -v2, v5, v4
	v_div_fmas_f32 v2, v2, v3, v5
	v_div_fixup_f32 v0, v2, v201, v0
	v_cvt_i32_f32_e32 v2, v0
	v_cmp_gt_f32_e32 vcc, s2, v0
	v_readfirstlane_b32 s2, v2
	s_add_i32 s4, s2, 1
	s_and_b64 s[2:3], vcc, exec
	s_cselect_b32 s2, s4, 0x2000
	s_sub_i32 s3, s34, s2
	s_add_i32 s2, s2, s34
	s_addk_i32 s2, 0x7f
	s_max_i32 s3, s3, 0
	s_min_i32 s2, s2, 0x1fff
	s_lshr_b32 s33, s3, 6
	s_ashr_i32 s4, s2, 6
	s_sub_i32 s2, s4, s33
	s_bitcmp1_b32 s2, 0
	s_cselect_b64 s[2:3], -1, 0
	s_and_b64 vcc, exec, s[2:3]
	s_cbranch_vccnz .LBB0_449
	s_cmpk_gt_i32 s4, 0x7e
	s_mov_b64 s[2:3], -1
	s_cbranch_scc0 .LBB0_446
	s_add_i32 s5, s33, -1
	s_mov_b64 s[2:3], 0

.LBB0_449:
	s_lshl_b32 s2, s48, 1
	s_sub_i32 s39, s2, s33
	s_add_i32 s3, s7, 0x2000
	s_or_b32 s2, s34, 64
	s_lshl_b32 s60, s33, 6
	s_add_i32 s5, s60, 0x80
	s_cmp_gt_i32 s39, 0
	s_cselect_b32 s62, s60, s5
	s_ashr_i32 s63, s62, 31
	s_lshl_b64 s[62:63], s[62:63], 12
	v_lshl_add_u64 v[2:3], v[202:203], 0, s[62:63]
	v_lshl_add_u64 v[6:7], v[2:3], 0, s[30:31]
	s_mov_b32 m0, s50
	v_lshl_add_u64 v[2:3], v[2:3], 0, s[36:37]
	global_load_lds_dwordx4 v[6:7], off
	s_mov_b32 m0, s51
	v_add_u32_e32 v35, v218, v149
	global_load_lds_dwordx4 v[2:3], off
	s_waitcnt vmcnt(6) lgkmcnt(0)
	s_barrier
	ds_read_b128 v[18:21], v35
	ds_read_b128 v[36:39], v35 offset:4096
	v_and_b32_e32 v155, 0x7fffffff, v1
	v_mov_b32_e32 v0, v201
	v_pk_mul_f32 v[16:17], v[170:171], v[0:1] op_sel_hi:[1,0] neg_lo:[0,1] neg_hi:[0,1]
	v_pk_mul_f32 v[14:15], v[168:169], v[0:1] op_sel_hi:[1,0] neg_lo:[0,1] neg_hi:[0,1]
	v_pk_mul_f32 v[12:13], v[166:167], v[0:1] op_sel_hi:[1,0] neg_lo:[0,1] neg_hi:[0,1]
	v_pk_mul_f32 v[10:11], v[164:165], v[0:1] op_sel_hi:[1,0] neg_lo:[0,1] neg_hi:[0,1]
	v_pk_mul_f32 v[8:9], v[162:163], v[0:1] op_sel_hi:[1,0] neg_lo:[0,1] neg_hi:[0,1]
	v_pk_mul_f32 v[6:7], v[158:159], v[0:1] op_sel_hi:[1,0] neg_lo:[0,1] neg_hi:[0,1]
	v_pk_mul_f32 v[4:5], v[156:157], v[0:1] op_sel_hi:[1,0] neg_lo:[0,1] neg_hi:[0,1]
	v_pk_mul_f32 v[2:3], v[154:155], v[0:1] op_sel_hi:[1,0] neg_lo:[0,1] neg_hi:[0,1]
	v_pk_mul_f32 v[32:33], v[192:193], v[0:1] op_sel_hi:[1,0] neg_lo:[0,1] neg_hi:[0,1]
	v_pk_mul_f32 v[30:31], v[190:191], v[0:1] op_sel_hi:[1,0] neg_lo:[0,1] neg_hi:[0,1]
	s_waitcnt vmcnt(0) lgkmcnt(0)
	v_mfma_f32_32x32x16_bf16 v[2:17], v[18:21], v[130:133], v[2:17]
	v_mul_f32_e64 v28, v188, -v0
	v_mul_f32_e64 v29, v189, -v0
	v_mul_f32_e64 v26, v186, -v0
	v_mul_f32_e64 v27, v187, -v0
	v_mul_f32_e64 v24, v184, -v0
	v_mul_f32_e64 v25, v185, -v0
	v_pk_mul_f32 v[22:23], v[176:177], v[0:1] op_sel_hi:[1,0] neg_lo:[0,1] neg_hi:[0,1]
	v_pk_mul_f32 v[20:21], v[174:175], v[0:1] op_sel_hi:[1,0] neg_lo:[0,1] neg_hi:[0,1]
	v_pk_mul_f32 v[18:19], v[172:173], v[0:1] op_sel_hi:[1,0] neg_lo:[0,1] neg_hi:[0,1]
	v_add_u32_e32 v48, v218, v208
	v_add_u32_e32 v49, v218, v209
	v_mfma_f32_32x32x16_bf16 v[18:33], v[36:39], v[130:133], v[18:33]
	ds_read_b128 v[36:39], v48
	ds_read_b128 v[40:43], v48 offset:4096
	v_add_u32_e32 v50, v218, v226
	s_sub_i32 s48, s4, s33
	s_cmp_gt_i32 s39, 1
	s_cselect_b32 s4, 1, 3
	s_add_i32 s4, s4, s33
	s_lshl_b32 s4, s4, 6
	s_waitcnt lgkmcnt(1)
	v_mfma_f32_32x32x16_bf16 v[2:17], v[36:39], v[134:137], v[2:17]
	s_ashr_i32 s5, s4, 31
	s_lshl_b64 s[4:5], s[4:5], 12
	s_mov_b32 m0, s7
	s_mov_b32 s10, 0
	s_waitcnt lgkmcnt(0)
	v_mfma_f32_32x32x16_bf16 v[18:33], v[40:43], v[134:137], v[18:33]
	ds_read_b128 v[36:39], v49
	ds_read_b128 v[40:43], v49 offset:4096
	s_waitcnt lgkmcnt(1)
	v_mfma_f32_32x32x16_bf16 v[2:17], v[36:39], v[138:141], v[2:17]
	ds_read_b128 v[36:39], v50
	s_waitcnt lgkmcnt(1)
	v_mfma_f32_32x32x16_bf16 v[18:33], v[40:43], v[138:141], v[18:33]
	ds_read_b128 v[40:43], v50 offset:4096
	s_waitcnt vmcnt(4) lgkmcnt(0)
	s_barrier
	s_waitcnt lgkmcnt(1)
	v_mfma_f32_32x32x16_bf16 v[2:17], v[36:39], v[142:145], v[2:17]
	v_lshl_add_u64 v[36:37], v[202:203], 0, s[4:5]
	v_lshl_add_u64 v[38:39], v[36:37], 0, s[30:31]
	global_load_lds_dwordx4 v[38:39], off
	v_lshl_add_u64 v[36:37], v[36:37], 0, s[36:37]
	s_mov_b32 m0, s3
	v_or_b32_e32 v38, s2, v148
	global_load_lds_dwordx4 v[36:37], off
	v_lshl_add_u64 v[36:37], v[44:45], 0, s[40:41]
	s_mov_b32 m0, s54
	s_waitcnt lgkmcnt(0)
	v_mfma_f32_32x32x16_bf16 v[18:33], v[40:43], v[142:145], v[18:33]
	global_load_lds_dwordx4 v[36:37], off
	v_lshl_add_u64 v[36:37], v[46:47], 0, s[40:41]
	s_mov_b32 m0, s55
	s_nop 0
	global_load_lds_dwordx4 v[36:37], off
	v_max3_f32 v36, v2, v3, v18
	v_max3_f32 v37, v4, v5, v19
	s_nop 15
	s_nop 15
	s_nop 15
	s_nop 0
	v_max3_f32 v36, v36, v20, v21
	v_max3_f32 v37, v37, v8, v9
	s_nop 0
	v_max3_f32 v36, v36, v6, v7
	v_max3_f32 v37, v37, v24, v25
	s_nop 0
	v_max3_f32 v36, v36, v22, v23
	v_max3_f32 v37, v37, v12, v13
	s_nop 0
	v_max3_f32 v36, v36, v10, v11
	v_max3_f32 v37, v37, v28, v29
	s_nop 0
	v_max3_f32 v36, v36, v26, v27
	v_max3_f32 v37, v37, v16, v17
	s_nop 0
	v_max3_f32 v36, v36, v14, v15
	v_max3_f32 v37, v37, v32, v33
	s_nop 0
	v_max3_f32 v36, v36, v30, v31
	s_nop 0
	v_max_f32_e32 v36, v36, v37
	s_nop 0
	v_mov_b32_e32 v37, v36
	s_nop 1
	v_permlane32_swap_b32 v36, v37
	s_nop 1
	s_nop 0
	v_max_f32_e32 v37, v37, v37
	v_max_f32_e32 v36, v36, v36
	v_max_f32_e32 v37, v36, v37
	v_sub_f32_e32 v2, v2, v37
	v_sub_f32_e32 v18, v18, v37
	v_sub_f32_e32 v3, v3, v37
	v_sub_f32_e32 v19, v19, v37
	v_sub_f32_e32 v4, v4, v37
	v_sub_f32_e32 v20, v20, v37
	v_sub_f32_e32 v5, v5, v37
	v_sub_f32_e32 v21, v21, v37
	v_sub_f32_e32 v6, v6, v37
	v_sub_f32_e32 v22, v22, v37
	v_sub_f32_e32 v7, v7, v37
	v_sub_f32_e32 v23, v23, v37
	v_sub_f32_e32 v8, v8, v37
	v_sub_f32_e32 v24, v24, v37
	v_sub_f32_e32 v9, v9, v37
	v_sub_f32_e32 v25, v25, v37
	v_sub_f32_e32 v10, v10, v37
	v_sub_f32_e32 v26, v26, v37
	v_sub_f32_e32 v11, v11, v37
	v_sub_f32_e32 v27, v27, v37
	v_sub_f32_e32 v12, v12, v37
	v_sub_f32_e32 v28, v28, v37
	v_sub_f32_e32 v13, v13, v37
	v_sub_f32_e32 v29, v29, v37
	v_sub_f32_e32 v14, v14, v37
	v_sub_f32_e32 v30, v30, v37
	v_sub_f32_e32 v15, v15, v37
	v_sub_f32_e32 v31, v31, v37
	v_sub_f32_e32 v16, v16, v37
	v_sub_f32_e32 v32, v32, v37
	v_sub_f32_e32 v17, v17, v37
	v_sub_f32_e32 v33, v33, v37
	v_exp_f32_e32 v52, v2
	v_exp_f32_e32 v53, v18
	v_exp_f32_e32 v54, v3
	v_exp_f32_e32 v55, v19
	v_exp_f32_e32 v56, v4
	v_exp_f32_e32 v57, v20
	v_exp_f32_e32 v58, v5
	v_exp_f32_e32 v59, v21
	v_exp_f32_e32 v60, v6
	v_exp_f32_e32 v61, v22
	v_exp_f32_e32 v62, v7
	v_exp_f32_e32 v63, v23
	v_exp_f32_e32 v64, v8
	v_exp_f32_e32 v65, v24
	v_exp_f32_e32 v101, v9
	v_exp_f32_e32 v102, v25
	v_exp_f32_e32 v103, v10
	v_exp_f32_e32 v104, v26
	v_exp_f32_e32 v114, v27
	v_exp_f32_e32 v105, v11
	v_exp_f32_e32 v107, v12
	v_exp_f32_e32 v115, v28
	v_exp_f32_e32 v108, v13
	v_exp_f32_e32 v116, v29
	v_exp_f32_e32 v109, v14
	v_exp_f32_e32 v117, v30
	ds_read_b128 v[10:13], v35 offset:16384
	v_exp_f32_e32 v118, v15
	v_exp_f32_e32 v119, v31
	ds_read_b128 v[2:5], v35 offset:20480
	v_exp_f32_e32 v35, v16
	v_exp_f32_e32 v120, v32
	ds_read_b128 v[6:9], v48 offset:16384
	v_exp_f32_e32 v121, v17
	v_exp_f32_e32 v122, v33
	ds_read_b128 v[14:17], v48 offset:20480
	ds_read_b128 v[18:21], v49 offset:16384
	ds_read_b128 v[22:25], v49 offset:20480
	ds_read_b128 v[26:29], v50 offset:16384
	ds_read_b128 v[30:33], v50 offset:20480
	v_add_f32_e32 v36, 0, v52
	v_add_f32_e32 v36, v53, v36
	v_add_f32_e32 v36, v54, v36
	v_add_f32_e32 v36, v55, v36
	v_add_f32_e32 v36, v56, v36
	v_add_f32_e32 v36, v57, v36
	v_add_f32_e32 v36, v58, v36
	v_add_f32_e32 v36, v59, v36
	v_add_f32_e32 v36, v60, v36
	v_add_f32_e32 v36, v61, v36
	v_add_f32_e32 v36, v62, v36
	v_add_f32_e32 v36, v63, v36
	v_add_f32_e32 v36, v64, v36
	v_add_f32_e32 v36, v65, v36
	v_add_f32_e32 v36, v101, v36
	v_add_f32_e32 v36, v102, v36
	v_add_f32_e32 v36, v103, v36
	v_add_f32_e32 v36, v104, v36
	v_add_f32_e32 v36, v105, v36
	v_add_f32_e32 v36, v114, v36
	v_add_f32_e32 v36, v107, v36
	v_add_f32_e32 v36, v115, v36
	v_add_f32_e32 v36, v108, v36
	v_add_f32_e32 v36, v116, v36
	v_add_f32_e32 v36, v109, v36
	v_add_f32_e32 v36, v117, v36
	v_add_f32_e32 v36, v118, v36
	v_add_f32_e32 v36, v119, v36
	v_add_f32_e32 v36, v35, v36
	v_add_f32_e32 v36, v120, v36
	v_add_f32_e32 v36, v121, v36
	v_add_f32_e32 v36, v122, v36
	v_sub_u32_e32 v82, v34, v38
	v_pk_add_f32 v[198:199], v[36:37], 0 op_sel_hi:[1,0]
	v_add_u32_e32 v36, -1, v82
	v_add_u32_e32 v37, -3, v82
	v_add_u32_e32 v38, -2, v82
	v_add_u32_e32 v39, -5, v82
	v_add_u32_e32 v40, -4, v82
	v_add_u32_e32 v41, -7, v82
	v_add_u32_e32 v42, -6, v82
	v_subrev_u32_e32 v43, 17, v82
	v_add_u32_e32 v44, -16, v82
	v_subrev_u32_e32 v45, 19, v82
	v_subrev_u32_e32 v46, 18, v82
	v_subrev_u32_e32 v47, 21, v82
	v_subrev_u32_e32 v48, 20, v82
	v_subrev_u32_e32 v49, 23, v82
	v_subrev_u32_e32 v50, 22, v82
	v_cvt_f32_i32_e32 v50, v50
	v_cvt_f32_i32_e32 v51, v49
	v_cvt_f32_i32_e32 v48, v48
	v_cvt_f32_i32_e32 v49, v47
	v_cvt_f32_i32_e32 v46, v46
	v_cvt_f32_i32_e32 v47, v45
	v_cvt_f32_i32_e32 v44, v44
	v_cvt_f32_i32_e32 v45, v43
	v_cvt_f32_i32_e32 v42, v42
	v_cvt_f32_i32_e32 v43, v41
	v_cvt_f32_i32_e32 v40, v40
	v_cvt_f32_i32_e32 v41, v39
	v_cvt_f32_i32_e32 v39, v82
	v_cvt_f32_i32_e32 v66, v36
	v_cvt_f32_i32_e32 v67, v37
	v_cvt_f32_i32_e32 v38, v38
	v_and_b32_e32 v36, 0x7fffffff, v39
	v_and_b32_e32 v37, 0x7fffffff, v66
	v_and_b32_e32 v39, 0x7fffffff, v67
	v_and_b32_e32 v38, 0x7fffffff, v38
	v_and_b32_e32 v41, 0x7fffffff, v41
	v_and_b32_e32 v40, 0x7fffffff, v40
	v_and_b32_e32 v43, 0x7fffffff, v43
	v_and_b32_e32 v42, 0x7fffffff, v42
	v_and_b32_e32 v45, 0x7fffffff, v45
	v_and_b32_e32 v44, 0x7fffffff, v44
	v_and_b32_e32 v47, 0x7fffffff, v47
	v_and_b32_e32 v46, 0x7fffffff, v46
	v_and_b32_e32 v49, 0x7fffffff, v49
	v_and_b32_e32 v48, 0x7fffffff, v48
	v_and_b32_e32 v51, 0x7fffffff, v51
	v_and_b32_e32 v50, 0x7fffffff, v50
	v_pk_fma_f32 v[80:81], v[0:1], v[50:51], v[198:199] op_sel:[0,0,1] op_sel_hi:[0,1,1] neg_lo:[1,0,1] neg_hi:[1,0,1]
	v_pk_fma_f32 v[78:79], v[0:1], v[48:49], v[198:199] op_sel:[0,0,1] op_sel_hi:[0,1,1] neg_lo:[1,0,1] neg_hi:[1,0,1]
	v_pk_fma_f32 v[76:77], v[0:1], v[46:47], v[198:199] op_sel:[0,0,1] op_sel_hi:[0,1,1] neg_lo:[1,0,1] neg_hi:[1,0,1]
	v_pk_fma_f32 v[74:75], v[0:1], v[44:45], v[198:199] op_sel:[0,0,1] op_sel_hi:[0,1,1] neg_lo:[1,0,1] neg_hi:[1,0,1]
	v_pk_fma_f32 v[72:73], v[0:1], v[42:43], v[198:199] op_sel:[0,0,1] op_sel_hi:[0,1,1] neg_lo:[1,0,1] neg_hi:[1,0,1]
	v_pk_fma_f32 v[70:71], v[0:1], v[40:41], v[198:199] op_sel:[0,0,1] op_sel_hi:[0,1,1] neg_lo:[1,0,1] neg_hi:[1,0,1]
	v_pk_fma_f32 v[68:69], v[0:1], v[38:39], v[198:199] op_sel:[0,0,1] op_sel_hi:[0,1,1] neg_lo:[1,0,1] neg_hi:[1,0,1]
	v_pk_fma_f32 v[66:67], v[0:1], v[36:37], v[198:199] op_sel:[0,0,1] op_sel_hi:[0,1,1] neg_lo:[1,0,1] neg_hi:[1,0,1]
	v_subrev_u32_e32 v36, 33, v82
	v_subrev_u32_e32 v37, 32, v82
	v_subrev_u32_e32 v38, 35, v82
	v_subrev_u32_e32 v39, 34, v82
	v_subrev_u32_e32 v40, 37, v82
	v_subrev_u32_e32 v41, 36, v82
	v_subrev_u32_e32 v42, 39, v82
	v_subrev_u32_e32 v43, 38, v82
	v_subrev_u32_e32 v44, 49, v82
	v_subrev_u32_e32 v45, 48, v82
	v_subrev_u32_e32 v46, 51, v82
	v_subrev_u32_e32 v47, 50, v82
	v_subrev_u32_e32 v48, 53, v82
	v_subrev_u32_e32 v49, 52, v82
	v_subrev_u32_e32 v50, 55, v82
	v_subrev_u32_e32 v51, 54, v82
	v_cvt_f32_i32_e32 v82, v51
	v_cvt_f32_i32_e32 v50, v50
	v_cvt_f32_i32_e32 v51, v49
	v_cvt_f32_i32_e32 v48, v48
	v_cvt_f32_i32_e32 v49, v47
	v_cvt_f32_i32_e32 v46, v46
	v_cvt_f32_i32_e32 v47, v45
	v_cvt_f32_i32_e32 v44, v44
	v_cvt_f32_i32_e32 v45, v43
	v_cvt_f32_i32_e32 v42, v42
	v_cvt_f32_i32_e32 v43, v41
	v_cvt_f32_i32_e32 v40, v40
	v_cvt_f32_i32_e32 v36, v36
	v_cvt_f32_i32_e32 v41, v37
	v_cvt_f32_i32_e32 v38, v38
	v_cvt_f32_i32_e32 v83, v39
	v_and_b32_e32 v37, 0x7fffffff, v36
	v_and_b32_e32 v36, 0x7fffffff, v41
	v_and_b32_e32 v39, 0x7fffffff, v38
	v_and_b32_e32 v38, 0x7fffffff, v83
	v_and_b32_e32 v41, 0x7fffffff, v40
	v_and_b32_e32 v40, 0x7fffffff, v43
	v_and_b32_e32 v43, 0x7fffffff, v42
	v_and_b32_e32 v42, 0x7fffffff, v45
	v_and_b32_e32 v45, 0x7fffffff, v44
	v_and_b32_e32 v44, 0x7fffffff, v47
	v_and_b32_e32 v47, 0x7fffffff, v46
	v_and_b32_e32 v46, 0x7fffffff, v49
	v_and_b32_e32 v49, 0x7fffffff, v48
	v_and_b32_e32 v48, 0x7fffffff, v51
	v_and_b32_e32 v51, 0x7fffffff, v50
	v_and_b32_e32 v50, 0x7fffffff, v82
	v_pk_fma_f32 v[96:97], v[0:1], v[50:51], v[198:199] op_sel:[0,0,1] op_sel_hi:[0,1,1] neg_lo:[1,0,1] neg_hi:[1,0,1]
	v_pk_fma_f32 v[94:95], v[0:1], v[48:49], v[198:199] op_sel:[0,0,1] op_sel_hi:[0,1,1] neg_lo:[1,0,1] neg_hi:[1,0,1]
	v_pk_fma_f32 v[92:93], v[0:1], v[46:47], v[198:199] op_sel:[0,0,1] op_sel_hi:[0,1,1] neg_lo:[1,0,1] neg_hi:[1,0,1]
	v_pk_fma_f32 v[90:91], v[0:1], v[44:45], v[198:199] op_sel:[0,0,1] op_sel_hi:[0,1,1] neg_lo:[1,0,1] neg_hi:[1,0,1]
	v_pk_fma_f32 v[88:89], v[0:1], v[42:43], v[198:199] op_sel:[0,0,1] op_sel_hi:[0,1,1] neg_lo:[1,0,1] neg_hi:[1,0,1]
	v_pk_fma_f32 v[86:87], v[0:1], v[40:41], v[198:199] op_sel:[0,0,1] op_sel_hi:[0,1,1] neg_lo:[1,0,1] neg_hi:[1,0,1]
	v_pk_fma_f32 v[84:85], v[0:1], v[38:39], v[198:199] op_sel:[0,0,1] op_sel_hi:[0,1,1] neg_lo:[1,0,1] neg_hi:[1,0,1]
	v_pk_fma_f32 v[82:83], v[0:1], v[36:37], v[198:199] op_sel:[0,0,1] op_sel_hi:[0,1,1] neg_lo:[1,0,1] neg_hi:[1,0,1]
	s_waitcnt lgkmcnt(0)
	v_mfma_f32_32x32x16_bf16 v[66:81], v[10:13], v[130:133], v[66:81]
	v_cvt_pk_bf16_f32 v98, v52, v54
	v_cvt_pk_bf16_f32 v99, v56, v58
	v_cvt_pk_bf16_f32 v100, v60, v62
	v_cvt_pk_bf16_f32 v101, v64, v101
	v_cvt_pk_bf16_f32 v110, v53, v55
	v_cvt_pk_bf16_f32 v111, v57, v59
	v_cvt_pk_bf16_f32 v112, v61, v63
	v_mfma_f32_32x32x16_bf16 v[82:97], v[2:5], v[130:133], v[82:97]
	v_cvt_pk_bf16_f32 v113, v65, v102
	v_cvt_pk_bf16_f32 v106, v103, v105
	v_cvt_pk_bf16_f32 v107, v107, v108
	v_cvt_pk_bf16_f32 v108, v109, v118
	v_cvt_pk_bf16_f32 v109, v35, v121
	v_cvt_pk_bf16_f32 v114, v104, v114
	v_cvt_pk_bf16_f32 v115, v115, v116
	v_mfma_f32_32x32x16_bf16 v[66:81], v[6:9], v[134:137], v[66:81]
	v_cvt_pk_bf16_f32 v116, v117, v119
	s_cmp_lt_i32 s48, 2
	v_cvt_pk_bf16_f32 v117, v120, v122
	v_mfma_f32_32x32x16_bf16 v[82:97], v[14:17], v[134:137], v[82:97]
	v_mfma_f32_32x32x16_bf16 v[66:81], v[18:21], v[138:141], v[66:81]
	v_mfma_f32_32x32x16_bf16 v[82:97], v[22:25], v[138:141], v[82:97]
	v_mfma_f32_32x32x16_bf16 v[66:81], v[26:29], v[142:145], v[66:81]
	v_mfma_f32_32x32x16_bf16 v[82:97], v[30:33], v[142:145], v[82:97]
	s_cbranch_scc1 .LBB0_472
	v_sub_u32_e32 v0, v148, v34
	v_cvt_f32_i32_e32 v155, v0
	v_mov_b32_e32 v16, v153
	v_mov_b32_e32 v17, v153
	v_mov_b32_e32 v2, v153
	v_mov_b32_e32 v3, v153
	v_mov_b32_e32 v4, v153
	v_mov_b32_e32 v5, v153
	v_mov_b32_e32 v6, v153
	v_mov_b32_e32 v7, v153
	v_mov_b32_e32 v8, v153
	v_mov_b32_e32 v9, v153
	v_mov_b32_e32 v10, v153
	v_mov_b32_e32 v11, v153
	v_mov_b32_e32 v12, v153
	v_mov_b32_e32 v13, v153
	v_mov_b32_e32 v14, v153
	v_mov_b32_e32 v15, v153
	v_mov_b64_e32 v[32:33], v[16:17]
	v_mov_b64_e32 v[48:49], v[16:17]
	v_mov_b64_e32 v[64:65], v[16:17]
	s_mov_b64 s[2:3], 0
	v_mov_b32_e32 v0, 1.0
	s_mov_b32 s62, 2
	s_mov_b32 s34, 5
	v_mov_b64_e32 v[30:31], v[14:15]
	v_mov_b64_e32 v[28:29], v[12:13]
	v_mov_b64_e32 v[26:27], v[10:11]
	v_mov_b64_e32 v[24:25], v[8:9]
	v_mov_b64_e32 v[22:23], v[6:7]
	v_mov_b64_e32 v[20:21], v[4:5]
	v_mov_b64_e32 v[18:19], v[2:3]
	v_mov_b64_e32 v[46:47], v[14:15]
	v_mov_b64_e32 v[44:45], v[12:13]
	v_mov_b64_e32 v[42:43], v[10:11]
	v_mov_b64_e32 v[40:41], v[8:9]
	v_mov_b64_e32 v[38:39], v[6:7]
	v_mov_b64_e32 v[36:37], v[4:5]
	v_mov_b64_e32 v[34:35], v[2:3]
	v_mov_b64_e32 v[62:63], v[14:15]
	v_mov_b64_e32 v[60:61], v[12:13]
	v_mov_b64_e32 v[58:59], v[10:11]
	v_mov_b64_e32 v[56:57], v[8:9]
	v_mov_b64_e32 v[54:55], v[6:7]
	v_mov_b64_e32 v[52:53], v[4:5]
	v_mov_b64_e32 v[50:51], v[2:3]
	s_add_i32 s61, s34, -2
	s_cmp_gt_i32 s61, s48
	s_mov_b64 s[4:5], -1
	s_cbranch_scc0 .LBB0_468
